# speedup vs baseline: 1.0317x; 1.0026x over previous
; DEVI void attn_item(const Params& p, int layer, int item, const int tid_) {
;     ...
;     const float lam = ((const float*)(p.ws + WS_MISC + 64))[layer];
;     const float li = 0.8f - 0.6f * __expf(-0.3f * (float)layer);
; DEVI void phase_attn(const Params& p, int layer, const int tid_) {
;   int* cnt = (int*)(p.ws + WS_MISC) + layer;
;   volatile int* slot = (volatile int*)(smem + ATT_SLOT);
;   for (;;) {
;     if (tid_ == 0) *slot = atomicAdd(cnt, 1);
;     __syncthreads();
;     const int item = __builtin_amdgcn_readfirstlane(*slot) + (layer == 0 ? 0 : IT_META);
;     __syncthreads();
;     if (item >= IT_TOTAL) break;
;     int tid2; asm volatile("v_mov_b32 %0, %1" : "=v"(tid2) : "v"(tid_));
;     attn_item(p, layer, item, tid2);
;   }
; }
.LBB0_126:
	s_cmp_eq_u32 s31, 4
	s_mov_b64 s[2:3], -1
	s_cbranch_scc0 .LBB0_264
	v_writelane_b32 v255, s31, 15
	v_readlane_b32 s4, v253, 2
	v_readlane_b32 s2, v255, 11
	s_mov_b32 s6, s2
	v_cvt_f32_u32_e32 v0, s6
	s_lshl_b32 s2, s2, 2
	v_readlane_b32 s5, v253, 3
	s_add_u32 s4, s4, s2
	s_addc_u32 s5, s5, 0
	v_mul_f32_e32 v0, 0xbe99999a, v0
	v_readlane_b32 s3, v255, 12
	v_writelane_b32 v255, s4, 17
	v_mul_f32_e32 v0, 0x3fb8aa3b, v0
	s_cmp_lt_u32 s39, 9
	v_writelane_b32 v255, s5, 18
	v_exp_f32_e32 v0, v0
	s_cselect_b32 s26, 0, 0xa0
	s_lshl_b32 s60, s6, 7
	v_readlane_b32 s4, v253, 14
	v_readlane_b32 s5, v253, 15
	s_add_u32 s28, s4, s2
	s_addc_u32 s29, s5, 0
	v_readlane_b32 s4, v254, 9
	v_mov_b32_e32 v2, 0xbf4ccccd
	s_lshl_b64 s[2:3], s[60:61], 2
	v_readlane_b32 s18, v254, 23
	v_fmamk_f32 v0, v0, 0x3f19999a, v2
	v_readlane_b32 s15, v254, 20
	v_readlane_b32 s17, v254, 22
	v_readlane_b32 s19, v254, 24
	s_add_u32 s30, s18, s2
	v_cmp_eq_u32_e64 s[24:25], 0, v146
	v_add_f32_e32 v147, 1.0, v0
	s_addc_u32 s31, s19, s3
	s_mov_b32 s15, 0xf800000
	s_mov_b32 s17, 0x42ddb3d8
	s_mov_b32 s18, 0x42b504f3
	v_readlane_b32 s5, v254, 10
	v_readlane_b32 s6, v254, 11
	v_readlane_b32 s7, v254, 12
	v_readlane_b32 s8, v254, 13
	v_readlane_b32 s9, v254, 14
	v_readlane_b32 s10, v254, 15
	v_readlane_b32 s11, v254, 16
	v_readlane_b32 s12, v254, 17
	v_readlane_b32 s13, v254, 18
	v_readlane_b32 s14, v254, 19
	v_readlane_b32 s16, v254, 21
	v_readlane_b32 s4, v254, 49
	s_nop 3
	s_bitcmp1_b32 s4, 8
	s_cbranch_scc0 .Lmy_prio_done
	s_setprio 1
.Lmy_prio_done:
	s_branch .LBB0_131
.LBB0_128:
	s_or_b64 exec, exec, s[4:5]

; #define SBAR() __builtin_amdgcn_sched_barrier(0)
; #define RD8(KS, P) const s16x4 P##l0 = tr_read<v_rd_off(0, KS, 0)>(vb), P##h0 = tr_read<v_rd_off(0, KS, 1)>(vb), P##l1 = tr_read<v_rd_off(1, KS, 0)>(vb), P##h1 = tr_read<v_rd_off(1, KS, 1)>(vb), \
;                                P##l2 = tr_read<v_rd_off(2, KS, 0)>(vb), P##h2 = tr_read<v_rd_off(2, KS, 1)>(vb), P##l3 = tr_read<v_rd_off(3, KS, 0)>(vb), P##h3 = tr_read<v_rd_off(3, KS, 1)>(vb)
; DEVI void pv_all(f32x16 (&o)[4], int vb, bf16x8 pa0, bf16x8 pa1, bf16x8 pa2, bf16x8 pa3) {
;     ...
;   RD8(0, a); RD8(1, b);
;   asm volatile("s_waitcnt lgkmcnt(8)" ::: "memory"); SBAR(); MM4(a, pa0); SBAR();
;   RD8(2, c);
;   asm volatile("s_waitcnt lgkmcnt(8)" ::: "memory"); SBAR(); MM4(b, pa1); SBAR();
;   RD8(3, d);
;   asm volatile("s_waitcnt lgkmcnt(8)" ::: "memory"); SBAR(); MM4(c, pa2); SBAR();
;   asm volatile("s_waitcnt lgkmcnt(0)" ::: "memory"); SBAR(); MM4(d, pa3);
.LBB0_191:
	v_lshl_add_u32 v0, s50, 14, v202
	ds_read_b64_tr_b16 v[80:81], v0 offset:0
	ds_read_b64_tr_b16 v[82:83], v0 offset:0x800
	ds_read_b64_tr_b16 v[84:85], v0 offset:0x200
	ds_read_b64_tr_b16 v[86:87], v0 offset:0xa00
	ds_read_b64_tr_b16 v[88:89], v0 offset:0x400
	ds_read_b64_tr_b16 v[90:91], v0 offset:0xc00
	ds_read_b64_tr_b16 v[92:93], v0 offset:0x600
	ds_read_b64_tr_b16 v[94:95], v0 offset:0xe00
	ds_read_b64_tr_b16 v[96:97], v0 offset:0x1000
	ds_read_b64_tr_b16 v[98:99], v0 offset:0x1800
	ds_read_b64_tr_b16 v[100:101], v0 offset:0x1200
	ds_read_b64_tr_b16 v[102:103], v0 offset:0x1a00
	ds_read_b64_tr_b16 v[104:105], v0 offset:0x1400
	ds_read_b64_tr_b16 v[106:107], v0 offset:0x1c00
	ds_read_b64_tr_b16 v[108:109], v0 offset:0x1600
	ds_read_b64_tr_b16 v[110:111], v0 offset:0x1e00
	s_waitcnt lgkmcnt(8)
	s_nop 2
	v_mfma_f32_32x32x16_bf16 v[64:79], v[80:83], v[128:131], v[64:79]
	v_mfma_f32_32x32x16_bf16 v[48:63], v[84:87], v[128:131], v[48:63]
	v_mfma_f32_32x32x16_bf16 v[32:47], v[88:91], v[128:131], v[32:47]
	v_mfma_f32_32x32x16_bf16 v[16:31], v[92:95], v[128:131], v[16:31]
	ds_read_b64_tr_b16 v[80:81], v0 offset:0x2000
	ds_read_b64_tr_b16 v[82:83], v0 offset:0x2800
	ds_read_b64_tr_b16 v[84:85], v0 offset:0x2200
	ds_read_b64_tr_b16 v[86:87], v0 offset:0x2a00
	ds_read_b64_tr_b16 v[88:89], v0 offset:0x2400
	ds_read_b64_tr_b16 v[90:91], v0 offset:0x2c00
	ds_read_b64_tr_b16 v[92:93], v0 offset:0x2600
	ds_read_b64_tr_b16 v[94:95], v0 offset:0x2e00
	s_waitcnt lgkmcnt(8)
	v_mfma_f32_32x32x16_bf16 v[64:79], v[96:99], v[10:13], v[64:79]
	v_mfma_f32_32x32x16_bf16 v[48:63], v[100:103], v[10:13], v[48:63]
	v_mfma_f32_32x32x16_bf16 v[32:47], v[104:107], v[10:13], v[32:47]
	v_mfma_f32_32x32x16_bf16 v[16:31], v[108:111], v[10:13], v[16:31]
	ds_read_b64_tr_b16 v[10:11], v0 offset:0x3000
	ds_read_b64_tr_b16 v[12:13], v0 offset:0x3800
	ds_read_b64_tr_b16 v[96:97], v0 offset:0x3200
	ds_read_b64_tr_b16 v[98:99], v0 offset:0x3a00
	ds_read_b64_tr_b16 v[100:101], v0 offset:0x3400
	ds_read_b64_tr_b16 v[102:103], v0 offset:0x3c00
	ds_read_b64_tr_b16 v[104:105], v0 offset:0x3600
	ds_read_b64_tr_b16 v[106:107], v0 offset:0x3e00
	s_waitcnt lgkmcnt(8)
	v_mfma_f32_32x32x16_bf16 v[64:79], v[80:83], v[6:9], v[64:79]
	v_mfma_f32_32x32x16_bf16 v[48:63], v[84:87], v[6:9], v[48:63]
	v_mfma_f32_32x32x16_bf16 v[32:47], v[88:91], v[6:9], v[32:47]
	v_mfma_f32_32x32x16_bf16 v[16:31], v[92:95], v[6:9], v[16:31]
	s_waitcnt lgkmcnt(6)
	v_mfma_f32_32x32x16_bf16 v[64:79], v[10:13], v[2:5], v[64:79]
	v_mov_b32_e32 v204, v14
	v_mov_b32_e32 v203, v15
	s_waitcnt lgkmcnt(4)
	v_mfma_f32_32x32x16_bf16 v[48:63], v[96:99], v[2:5], v[48:63]
	s_waitcnt lgkmcnt(2)
	v_mfma_f32_32x32x16_bf16 v[32:47], v[100:103], v[2:5], v[32:47]
	s_waitcnt lgkmcnt(0)
	v_mfma_f32_32x32x16_bf16 v[16:31], v[104:107], v[2:5], v[16:31]

; #define SBAR() __builtin_amdgcn_sched_barrier(0)
; #define RD8(KS, P) const s16x4 P##l0 = tr_read<v_rd_off(0, KS, 0)>(vb), P##h0 = tr_read<v_rd_off(0, KS, 1)>(vb), P##l1 = tr_read<v_rd_off(1, KS, 0)>(vb), P##h1 = tr_read<v_rd_off(1, KS, 1)>(vb), \
;                                P##l2 = tr_read<v_rd_off(2, KS, 0)>(vb), P##h2 = tr_read<v_rd_off(2, KS, 1)>(vb), P##l3 = tr_read<v_rd_off(3, KS, 0)>(vb), P##h3 = tr_read<v_rd_off(3, KS, 1)>(vb)
; DEVI void pv_all(f32x16 (&o)[4], int vb, bf16x8 pa0, bf16x8 pa1, bf16x8 pa2, bf16x8 pa3) {
;     ...
;   RD8(0, a); RD8(1, b);
;   asm volatile("s_waitcnt lgkmcnt(8)" ::: "memory"); SBAR(); MM4(a, pa0); SBAR();
;   RD8(2, c);
;   asm volatile("s_waitcnt lgkmcnt(8)" ::: "memory"); SBAR(); MM4(b, pa1); SBAR();
;   RD8(3, d);
;   asm volatile("s_waitcnt lgkmcnt(8)" ::: "memory"); SBAR(); MM4(c, pa2); SBAR();
;   asm volatile("s_waitcnt lgkmcnt(0)" ::: "memory"); SBAR(); MM4(d, pa3);
; template <bool ALIBI, bool LAST>
; DEVI void softmax_tile(f32x16& p0, f32x16& p1, const float C, const float nslope2, const float dbase, float& m_reg, float& l_reg, float& alpha,
;                        bf16x8& pa0, bf16x8& pa1, bf16x8& pa2, bf16x8& pa3) {
;     ...
;   {
;     const float mnC = -m_reg * C;
; #pragma unroll
;     for (int r = 0; r < 16; ++r) { p0[r] = __builtin_amdgcn_exp2f(fmaf(p0[r], C, mnC)); p1[r] = __builtin_amdgcn_exp2f(fmaf(p1[r], C, mnC)); }
;   }
;   float ps = 0.f;
; #pragma unroll
;   for (int r = 0; r < 16; ++r) ps += p0[r];
; #pragma unroll
;   for (int r = 0; r < 16; ++r) ps += p1[r];
;   { auto rr = __builtin_amdgcn_permlane32_swap(__float_as_uint(ps), __float_as_uint(ps), false, false);
;     ps = __uint_as_float(rr[0]) + __uint_as_float(rr[1]); }
;   l_reg = l_reg * alpha + ps;
;     ...
;   PK4(p0, 0, pa0); PK4(p0, 8, pa1); PK4(p1, 0, pa2); PK4(p1, 8, pa3);
.Lmy_B_cont:
	v_mul_f32_e32 v238, 0xbdd53b94, v199
	ds_read_b64_tr_b16 v[220:221], v236 offset:0x1000
	ds_read_b64_tr_b16 v[222:223], v236 offset:0x1800
	ds_read_b64_tr_b16 v[224:225], v236 offset:0x1200
	ds_read_b64_tr_b16 v[226:227], v236 offset:0x1a00
	ds_read_b64_tr_b16 v[228:229], v236 offset:0x1400
	ds_read_b64_tr_b16 v[230:231], v236 offset:0x1c00
	ds_read_b64_tr_b16 v[232:233], v236 offset:0x1600
	ds_read_b64_tr_b16 v[234:235], v236 offset:0x1e00
	v_fmamk_f32 v82, v82, 0x3dd53b94, v238
	v_fmamk_f32 v83, v83, 0x3dd53b94, v238
	v_exp_f32_e32 v82, v82
	v_fmamk_f32 v84, v84, 0x3dd53b94, v238
	v_exp_f32_e32 v83, v83
	v_fmamk_f32 v85, v85, 0x3dd53b94, v238
	v_exp_f32_e32 v84, v84
	v_fmamk_f32 v86, v86, 0x3dd53b94, v238
	v_exp_f32_e32 v85, v85
	v_add_f32_e32 v237, v82, v83
	v_fmamk_f32 v87, v87, 0x3dd53b94, v238
	v_exp_f32_e32 v86, v86
	v_add_f32_e32 v237, v84, v237
	v_fmamk_f32 v88, v88, 0x3dd53b94, v238
	v_exp_f32_e32 v87, v87
	v_add_f32_e32 v237, v85, v237
	v_fmamk_f32 v89, v89, 0x3dd53b94, v238
	v_exp_f32_e32 v88, v88
	v_add_f32_e32 v237, v86, v237
	v_fmamk_f32 v90, v90, 0x3dd53b94, v238
	v_exp_f32_e32 v89, v89
	v_add_f32_e32 v237, v87, v237
	v_fmamk_f32 v91, v91, 0x3dd53b94, v238
	v_exp_f32_e32 v90, v90
	v_add_f32_e32 v237, v88, v237
	v_fmamk_f32 v92, v92, 0x3dd53b94, v238
	v_exp_f32_e32 v91, v91
	v_add_f32_e32 v237, v89, v237
	v_fmamk_f32 v93, v93, 0x3dd53b94, v238
	v_exp_f32_e32 v92, v92
	v_add_f32_e32 v237, v90, v237
	v_cvt_pk_bf16_f32 v89, v88, v89
	v_fmamk_f32 v94, v94, 0x3dd53b94, v238
	v_exp_f32_e32 v93, v93
	v_add_f32_e32 v237, v91, v237
	v_cvt_pk_bf16_f32 v88, v86, v87
	v_fmamk_f32 v95, v95, 0x3dd53b94, v238
	v_exp_f32_e32 v94, v94
	v_add_f32_e32 v237, v92, v237
	v_cvt_pk_bf16_f32 v87, v84, v85
	v_fmamk_f32 v96, v96, 0x3dd53b94, v238
	v_exp_f32_e32 v95, v95
	v_add_f32_e32 v237, v93, v237
	v_cvt_pk_bf16_f32 v86, v82, v83
	v_fmamk_f32 v97, v97, 0x3dd53b94, v238
	v_exp_f32_e32 v96, v96
	v_add_f32_e32 v237, v94, v237
	v_fmamk_f32 v66, v66, 0x3dd53b94, v238
	v_exp_f32_e32 v97, v97
	v_add_f32_e32 v237, v95, v237
	v_permlane32_swap_b32_e32 v86, v88
	v_fmamk_f32 v67, v67, 0x3dd53b94, v238
	v_exp_f32_e32 v66, v66
	v_add_f32_e32 v237, v96, v237
	v_permlane32_swap_b32_e32 v87, v89
	v_fmamk_f32 v68, v68, 0x3dd53b94, v238
	v_exp_f32_e32 v67, v67
	v_add_f32_e32 v237, v97, v237
	s_waitcnt lgkmcnt(8)
	v_mfma_f32_32x32x16_bf16 v[2:17], v[204:207], v[86:89], v[2:17]
	v_fmamk_f32 v69, v69, 0x3dd53b94, v238
	v_exp_f32_e32 v68, v68
	v_add_f32_e32 v237, v66, v237
	v_cvt_pk_bf16_f32 v97, v96, v97
	v_fmamk_f32 v70, v70, 0x3dd53b94, v238
	v_exp_f32_e32 v69, v69
	v_add_f32_e32 v237, v67, v237
	v_cvt_pk_bf16_f32 v96, v94, v95
	v_mfma_f32_32x32x16_bf16 v[18:33], v[208:211], v[86:89], v[18:33]
	v_fmamk_f32 v71, v71, 0x3dd53b94, v238
	v_exp_f32_e32 v70, v70
	v_add_f32_e32 v237, v68, v237
	v_cvt_pk_bf16_f32 v95, v92, v93
	v_fmamk_f32 v72, v72, 0x3dd53b94, v238
	v_exp_f32_e32 v71, v71
	v_add_f32_e32 v237, v69, v237
	v_cvt_pk_bf16_f32 v94, v90, v91
	v_mfma_f32_32x32x16_bf16 v[34:49], v[212:215], v[86:89], v[34:49]
	v_fmamk_f32 v73, v73, 0x3dd53b94, v238
	v_exp_f32_e32 v72, v72
	v_add_f32_e32 v237, v70, v237
	v_fmamk_f32 v74, v74, 0x3dd53b94, v238
	v_exp_f32_e32 v73, v73
	v_add_f32_e32 v237, v71, v237
	v_permlane32_swap_b32_e32 v94, v96
	v_mfma_f32_32x32x16_bf16 v[50:65], v[216:219], v[86:89], v[50:65]
	ds_read_b64_tr_b16 v[204:205], v236 offset:0x2000
	ds_read_b64_tr_b16 v[206:207], v236 offset:0x2800
	ds_read_b64_tr_b16 v[208:209], v236 offset:0x2200
	ds_read_b64_tr_b16 v[210:211], v236 offset:0x2a00
	ds_read_b64_tr_b16 v[212:213], v236 offset:0x2400
	ds_read_b64_tr_b16 v[214:215], v236 offset:0x2c00
	ds_read_b64_tr_b16 v[216:217], v236 offset:0x2600
	ds_read_b64_tr_b16 v[218:219], v236 offset:0x2e00
	v_fmamk_f32 v75, v75, 0x3dd53b94, v238
	v_exp_f32_e32 v74, v74
	v_add_f32_e32 v237, v72, v237
	v_permlane32_swap_b32_e32 v95, v97
	v_fmamk_f32 v76, v76, 0x3dd53b94, v238
	v_exp_f32_e32 v75, v75
	v_add_f32_e32 v237, v73, v237
	s_waitcnt lgkmcnt(8)
	v_mfma_f32_32x32x16_bf16 v[2:17], v[220:223], v[94:97], v[2:17]
	v_fmamk_f32 v77, v77, 0x3dd53b94, v238
	v_exp_f32_e32 v76, v76
	v_add_f32_e32 v237, v74, v237
	v_cvt_pk_bf16_f32 v73, v72, v73
	v_fmamk_f32 v78, v78, 0x3dd53b94, v238
	v_exp_f32_e32 v77, v77
	v_add_f32_e32 v237, v75, v237
	v_cvt_pk_bf16_f32 v72, v70, v71
	v_mfma_f32_32x32x16_bf16 v[18:33], v[224:227], v[94:97], v[18:33]
	v_fmamk_f32 v79, v79, 0x3dd53b94, v238
	v_exp_f32_e32 v78, v78
	v_add_f32_e32 v237, v76, v237
	v_cvt_pk_bf16_f32 v71, v68, v69
	v_fmamk_f32 v80, v80, 0x3dd53b94, v238
	v_exp_f32_e32 v79, v79
	v_add_f32_e32 v237, v77, v237
	v_cvt_pk_bf16_f32 v70, v66, v67
	v_mfma_f32_32x32x16_bf16 v[34:49], v[228:231], v[94:97], v[34:49]
	v_fmamk_f32 v81, v81, 0x3dd53b94, v238
	v_exp_f32_e32 v80, v80
	v_add_f32_e32 v237, v78, v237
	v_exp_f32_e32 v81, v81
	v_add_f32_e32 v237, v79, v237
	v_mfma_f32_32x32x16_bf16 v[50:65], v[232:235], v[94:97], v[50:65]
	ds_read_b64_tr_b16 v[220:221], v236 offset:0x3000
	ds_read_b64_tr_b16 v[222:223], v236 offset:0x3800
	ds_read_b64_tr_b16 v[224:225], v236 offset:0x3200
	ds_read_b64_tr_b16 v[226:227], v236 offset:0x3a00
	ds_read_b64_tr_b16 v[228:229], v236 offset:0x3400
	ds_read_b64_tr_b16 v[230:231], v236 offset:0x3c00
	ds_read_b64_tr_b16 v[232:233], v236 offset:0x3600
	ds_read_b64_tr_b16 v[234:235], v236 offset:0x3e00
	v_permlane32_swap_b32_e32 v70, v72
	v_add_f32_e32 v237, v80, v237
	v_permlane32_swap_b32_e32 v71, v73
	v_add_f32_e32 v237, v81, v237
	v_cvt_pk_bf16_f32 v81, v80, v81
	s_waitcnt lgkmcnt(8)
	v_mfma_f32_32x32x16_bf16 v[2:17], v[204:207], v[70:73], v[2:17]
	v_cvt_pk_bf16_f32 v80, v78, v79
	v_cvt_pk_bf16_f32 v79, v76, v77
	v_mfma_f32_32x32x16_bf16 v[18:33], v[208:211], v[70:73], v[18:33]
	v_cvt_pk_bf16_f32 v78, v74, v75
	v_mov_b32_e32 v169, v237
	v_mfma_f32_32x32x16_bf16 v[34:49], v[212:215], v[70:73], v[34:49]
	v_permlane32_swap_b32_e32 v78, v80
	v_permlane32_swap_b32_e32 v79, v81
	v_permlane32_swap_b32_e32 v237, v169
	v_mfma_f32_32x32x16_bf16 v[50:65], v[216:219], v[70:73], v[50:65]
	v_add_f32_e32 v169, v237, v169
	v_fmac_f32_e32 v169, v149, v168
	v_mov_b32_e32 v149, v169
	s_waitcnt lgkmcnt(6)
	v_mfma_f32_32x32x16_bf16 v[2:17], v[220:223], v[78:81], v[2:17]
	s_waitcnt lgkmcnt(4)
	v_mfma_f32_32x32x16_bf16 v[18:33], v[224:227], v[78:81], v[18:33]
	s_waitcnt lgkmcnt(2)
	v_mfma_f32_32x32x16_bf16 v[34:49], v[228:231], v[78:81], v[34:49]
	s_waitcnt lgkmcnt(0)
	v_mfma_f32_32x32x16_bf16 v[50:65], v[232:235], v[78:81], v[50:65]
	s_branch .LBB0_210

; #define SBAR() __builtin_amdgcn_sched_barrier(0)
; template <int DQK, bool ALIBI>
; DEVI void attn_pass(const AttnArgs& a, f32x16 (&o)[4], const int tid_) {
;     ...
;       const unsigned char* Ks = K_lds + buf * SHM_K + r32 * KPITCH;
;       const int key = KKEY(r32);
;     ...
;       if constexpr (DQK == 128 || DQK == 64 || DQK == 192) {
;         constexpr int NG4 = DQK / 64;
;         bf16x8 ka[4][2], kb[4][2];
; #pragma unroll
;         for (int s = 0; s < 4; ++s) { ka[s][0] = *(const bf16x8*)(Ks + KCB(s)); ka[s][1] = *(const bf16x8*)(Ks + 32 * KPITCH + KCB(s)); }
;         SBAR();
; #pragma unroll
;         for (int g = 0; g < NG4; ++g) {
;           if (g + 1 < NG4) {
; #pragma unroll
;             for (int s = 0; s < 4; ++s) { const int d1 = (g + 1) * 4 + s;
;               if (g & 1) { ka[s][0] = *(const bf16x8*)(Ks + KCB(d1)); ka[s][1] = *(const bf16x8*)(Ks + 32 * KPITCH + KCB(d1)); }
;               else       { kb[s][0] = *(const bf16x8*)(Ks + KCB(d1)); kb[s][1] = *(const bf16x8*)(Ks + 32 * KPITCH + KCB(d1)); } }
;           }
; #pragma unroll
;           for (int s = 0; s < 4; ++s) { const int d0 = g * 4 + s;
;             p0 = __builtin_amdgcn_mfma_f32_32x32x16_bf16((g & 1) ? kb[s][0] : ka[s][0], qr[d0], p0, 0, 0, 0);
;             p1 = __builtin_amdgcn_mfma_f32_32x32x16_bf16((g & 1) ? kb[s][1] : ka[s][1], qr[d0], p1, 0, 0, 0); }
;           SBAR();
.LBB0_233:
	s_and_saveexec_b64 s[12:13], s[4:5]
	s_cbranch_execz .LBB0_227
	s_lshl_b32 s34, s34, 14
	v_add_u32_e32 v144, s34, v148
	v_add_u32_e32 v70, v144, v158
	v_add_u32_e32 v74, v144, v159
	ds_read_b128 v[66:69], v70 offset:32768
	ds_read_b128 v[70:73], v70 offset:40960
	ds_read_b128 v[160:163], v74 offset:32768
	ds_read_b128 v[164:167], v74 offset:40960
	v_add_u32_e32 v74, v144, v156
	ds_read_b128 v[184:187], v74 offset:32768
	ds_read_b128 v[188:191], v74 offset:40960
	v_add_u32_e32 v74, v144, v157
	ds_read_b128 v[192:195], v74 offset:32768
	ds_read_b128 v[196:199], v74 offset:40960
	s_waitcnt lgkmcnt(6)
	v_mfma_f32_32x32x16_bf16 v[82:97], v[66:69], v[126:129], 0
	v_add_u32_e32 v168, v144, v153
	v_mfma_f32_32x32x16_bf16 v[66:81], v[70:73], v[126:129], 0
	s_waitcnt lgkmcnt(4)
	v_mfma_f32_32x32x16_bf16 v[82:97], v[160:163], v[122:125], v[82:97]
	v_mfma_f32_32x32x16_bf16 v[66:81], v[164:167], v[122:125], v[66:81]
	v_add_u32_e32 v164, v144, v155
	ds_read_b128 v[160:163], v164 offset:32768
	ds_read_b128 v[164:167], v164 offset:40960
	s_waitcnt lgkmcnt(4)
	v_mfma_f32_32x32x16_bf16 v[82:97], v[184:187], v[118:121], v[82:97]
	v_mfma_f32_32x32x16_bf16 v[66:81], v[188:191], v[118:121], v[66:81]
	ds_read_b128 v[184:187], v168 offset:32768
	ds_read_b128 v[188:191], v168 offset:40960
	v_add_u32_e32 v168, v144, v152
	v_add_u32_e32 v144, v144, v154
	s_waitcnt lgkmcnt(4)
	v_mfma_f32_32x32x16_bf16 v[82:97], v[192:195], v[114:117], v[82:97]
	ds_read_b128 v[192:195], v168 offset:32768
	ds_read_b128 v[200:203], v168 offset:40960
	ds_read_b128 v[204:207], v144 offset:32768
	ds_read_b128 v[208:211], v144 offset:40960
	v_mfma_f32_32x32x16_bf16 v[66:81], v[196:199], v[114:117], v[66:81]
	s_waitcnt lgkmcnt(6)
	v_mfma_f32_32x32x16_bf16 v[82:97], v[160:163], v[110:113], v[82:97]
	v_mfma_f32_32x32x16_bf16 v[66:81], v[164:167], v[110:113], v[66:81]
	s_waitcnt lgkmcnt(4)
	v_mfma_f32_32x32x16_bf16 v[82:97], v[184:187], v[106:109], v[82:97]
	v_mfma_f32_32x32x16_bf16 v[66:81], v[188:191], v[106:109], v[66:81]
	s_waitcnt lgkmcnt(2)
	v_mfma_f32_32x32x16_bf16 v[82:97], v[192:195], v[102:105], v[82:97]
	v_mfma_f32_32x32x16_bf16 v[66:81], v[200:203], v[102:105], v[66:81]
	s_waitcnt lgkmcnt(0)
	v_mfma_f32_32x32x16_bf16 v[82:97], v[204:207], v[98:101], v[82:97]
	v_mfma_f32_32x32x16_bf16 v[66:81], v[208:211], v[98:101], v[66:81]
	v_add_u32_e32 v211, s34, v145
	ds_read_b64_tr_b16 v[192:193], v211 offset:0x0
	ds_read_b64_tr_b16 v[194:195], v211 offset:0x800
	ds_read_b64_tr_b16 v[196:197], v211 offset:0x200
	ds_read_b64_tr_b16 v[198:199], v211 offset:0xa00
	ds_read_b64_tr_b16 v[200:201], v211 offset:0x400
	ds_read_b64_tr_b16 v[202:203], v211 offset:0xc00
	ds_read_b64_tr_b16 v[204:205], v211 offset:0x600
	ds_read_b64_tr_b16 v[206:207], v211 offset:0xe00
	s_nop 1
	v_max3_f32 v144, v82, v83, v84
	v_max3_f32 v144, v144, v85, v86
	v_max3_f32 v144, v144, v87, v88
	v_max3_f32 v144, v144, v89, v90
	v_max3_f32 v144, v144, v91, v92
	v_max3_f32 v144, v144, v93, v94
	v_max3_f32 v144, v144, v95, v96
	v_max3_f32 v144, v144, v97, v66
	v_max3_f32 v144, v144, v67, v68
	v_max3_f32 v144, v144, v69, v70
	v_max3_f32 v144, v144, v71, v72
	v_max3_f32 v144, v144, v73, v74
	v_max3_f32 v144, v144, v75, v76
	v_max3_f32 v144, v144, v77, v78
	v_max3_f32 v144, v144, v79, v80
	v_max_f32_e32 v144, v144, v81
	v_mov_b32_e32 v160, v144
	s_nop 1
	v_permlane32_swap_b32_e32 v144, v160
	v_max_f32_e32 v144, v144, v160
	v_sub_f32_e32 v160, v144, v151
	v_cmp_ge_f32_e32 vcc, s18, v160
	s_cmp_eq_u64 vcc, exec
	s_cbranch_scc0 .Lmy_A_slow
	v_mov_b32_e32 v144, 1.0
; #define SBAR() __builtin_amdgcn_sched_barrier(0)
; #define RD8(KS, P) const s16x4 P##l0 = tr_read<v_rd_off(0, KS, 0)>(vb), P##h0 = tr_read<v_rd_off(0, KS, 1)>(vb), P##l1 = tr_read<v_rd_off(1, KS, 0)>(vb), P##h1 = tr_read<v_rd_off(1, KS, 1)>(vb), \
;                                P##l2 = tr_read<v_rd_off(2, KS, 0)>(vb), P##h2 = tr_read<v_rd_off(2, KS, 1)>(vb), P##l3 = tr_read<v_rd_off(3, KS, 0)>(vb), P##h3 = tr_read<v_rd_off(3, KS, 1)>(vb)
; DEVI void pv_all(f32x16 (&o)[4], int vb, bf16x8 pa0, bf16x8 pa1, bf16x8 pa2, bf16x8 pa3) {
;     ...
;   RD8(0, a); RD8(1, b);
;   asm volatile("s_waitcnt lgkmcnt(8)" ::: "memory"); SBAR(); MM4(a, pa0); SBAR();
;   RD8(2, c);
;   asm volatile("s_waitcnt lgkmcnt(8)" ::: "memory"); SBAR(); MM4(b, pa1); SBAR();
;   RD8(3, d);
;   asm volatile("s_waitcnt lgkmcnt(8)" ::: "memory"); SBAR(); MM4(c, pa2); SBAR();
;   asm volatile("s_waitcnt lgkmcnt(0)" ::: "memory"); SBAR(); MM4(d, pa3);
; template <bool ALIBI, bool LAST>
; DEVI void softmax_tile(f32x16& p0, f32x16& p1, const float C, const float nslope2, const float dbase, float& m_reg, float& l_reg, float& alpha,
;                        bf16x8& pa0, bf16x8& pa1, bf16x8& pa2, bf16x8& pa3) {
;     ...
;   {
;     const float mnC = -m_reg * C;
; #pragma unroll
;     for (int r = 0; r < 16; ++r) { p0[r] = __builtin_amdgcn_exp2f(fmaf(p0[r], C, mnC)); p1[r] = __builtin_amdgcn_exp2f(fmaf(p1[r], C, mnC)); }
;   }
;   float ps = 0.f;
; #pragma unroll
;   for (int r = 0; r < 16; ++r) ps += p0[r];
; #pragma unroll
;   for (int r = 0; r < 16; ++r) ps += p1[r];
;   { auto rr = __builtin_amdgcn_permlane32_swap(__float_as_uint(ps), __float_as_uint(ps), false, false);
;     ps = __uint_as_float(rr[0]) + __uint_as_float(rr[1]); }
;   l_reg = l_reg * alpha + ps;
;     ...
;   PK4(p0, 0, pa0); PK4(p0, 8, pa1); PK4(p1, 0, pa2); PK4(p1, 8, pa3);
.Lmy_A_cont:
	v_mul_f32_e32 v208, 0xbe0293ee, v151
	ds_read_b64_tr_b16 v[160:161], v211 offset:0x1000
	ds_read_b64_tr_b16 v[162:163], v211 offset:0x1800
	ds_read_b64_tr_b16 v[164:165], v211 offset:0x1200
	ds_read_b64_tr_b16 v[166:167], v211 offset:0x1a00
	ds_read_b64_tr_b16 v[184:185], v211 offset:0x1400
	ds_read_b64_tr_b16 v[186:187], v211 offset:0x1c00
	ds_read_b64_tr_b16 v[188:189], v211 offset:0x1600
	ds_read_b64_tr_b16 v[190:191], v211 offset:0x1e00
	v_fmamk_f32 v82, v82, 0x3e0293ee, v208
	v_fmamk_f32 v83, v83, 0x3e0293ee, v208
	v_exp_f32_e32 v82, v82
	v_fmamk_f32 v84, v84, 0x3e0293ee, v208
	v_exp_f32_e32 v83, v83
	v_fmamk_f32 v85, v85, 0x3e0293ee, v208
	v_exp_f32_e32 v84, v84
	v_fmamk_f32 v86, v86, 0x3e0293ee, v208
	v_exp_f32_e32 v85, v85
	v_add_f32_e32 v210, v82, v83
	v_fmamk_f32 v87, v87, 0x3e0293ee, v208
	v_exp_f32_e32 v86, v86
	v_add_f32_e32 v210, v84, v210
	v_fmamk_f32 v88, v88, 0x3e0293ee, v208
	v_exp_f32_e32 v87, v87
	v_add_f32_e32 v210, v85, v210
	v_fmamk_f32 v89, v89, 0x3e0293ee, v208
	v_exp_f32_e32 v88, v88
	v_add_f32_e32 v210, v86, v210
	v_fmamk_f32 v90, v90, 0x3e0293ee, v208
	v_exp_f32_e32 v89, v89
	v_add_f32_e32 v210, v87, v210
	v_fmamk_f32 v91, v91, 0x3e0293ee, v208
	v_exp_f32_e32 v90, v90
	v_add_f32_e32 v210, v88, v210
	v_fmamk_f32 v92, v92, 0x3e0293ee, v208
	v_exp_f32_e32 v91, v91
	v_add_f32_e32 v210, v89, v210
	v_fmamk_f32 v93, v93, 0x3e0293ee, v208
	v_exp_f32_e32 v92, v92
	v_add_f32_e32 v210, v90, v210
	v_cvt_pk_bf16_f32 v89, v88, v89
	v_fmamk_f32 v94, v94, 0x3e0293ee, v208
	v_exp_f32_e32 v93, v93
	v_add_f32_e32 v210, v91, v210
	v_cvt_pk_bf16_f32 v88, v86, v87
	v_fmamk_f32 v95, v95, 0x3e0293ee, v208
	v_exp_f32_e32 v94, v94
	v_add_f32_e32 v210, v92, v210
	v_cvt_pk_bf16_f32 v87, v84, v85
	v_fmamk_f32 v96, v96, 0x3e0293ee, v208
	v_exp_f32_e32 v95, v95
	v_add_f32_e32 v210, v93, v210
	v_cvt_pk_bf16_f32 v86, v82, v83
	v_fmamk_f32 v97, v97, 0x3e0293ee, v208
	v_exp_f32_e32 v96, v96
	v_add_f32_e32 v210, v94, v210
	v_fmamk_f32 v66, v66, 0x3e0293ee, v208
	v_exp_f32_e32 v97, v97
	v_add_f32_e32 v210, v95, v210
	v_permlane32_swap_b32_e32 v86, v88
	v_fmamk_f32 v67, v67, 0x3e0293ee, v208
	v_exp_f32_e32 v66, v66
	v_add_f32_e32 v210, v96, v210
	v_permlane32_swap_b32_e32 v87, v89
	v_fmamk_f32 v68, v68, 0x3e0293ee, v208
	v_exp_f32_e32 v67, v67
	v_add_f32_e32 v210, v97, v210
	s_waitcnt lgkmcnt(8)
	v_mfma_f32_32x32x16_bf16 v[2:17], v[192:195], v[86:89], v[2:17]
	v_fmamk_f32 v69, v69, 0x3e0293ee, v208
	v_exp_f32_e32 v68, v68
	v_add_f32_e32 v210, v66, v210
	v_cvt_pk_bf16_f32 v97, v96, v97
	v_fmamk_f32 v70, v70, 0x3e0293ee, v208
	v_exp_f32_e32 v69, v69
	v_add_f32_e32 v210, v67, v210
	v_cvt_pk_bf16_f32 v96, v94, v95
	v_mfma_f32_32x32x16_bf16 v[18:33], v[196:199], v[86:89], v[18:33]
	v_fmamk_f32 v71, v71, 0x3e0293ee, v208
	v_exp_f32_e32 v70, v70
	v_add_f32_e32 v210, v68, v210
	v_cvt_pk_bf16_f32 v95, v92, v93
	v_fmamk_f32 v72, v72, 0x3e0293ee, v208
	v_exp_f32_e32 v71, v71
	v_add_f32_e32 v210, v69, v210
	v_cvt_pk_bf16_f32 v94, v90, v91
	v_mfma_f32_32x32x16_bf16 v[34:49], v[200:203], v[86:89], v[34:49]
	v_fmamk_f32 v73, v73, 0x3e0293ee, v208
	v_exp_f32_e32 v72, v72
	v_add_f32_e32 v210, v70, v210
	v_fmamk_f32 v74, v74, 0x3e0293ee, v208
	v_exp_f32_e32 v73, v73
	v_add_f32_e32 v210, v71, v210
	v_permlane32_swap_b32_e32 v94, v96
	v_mfma_f32_32x32x16_bf16 v[50:65], v[204:207], v[86:89], v[50:65]
	ds_read_b64_tr_b16 v[192:193], v211 offset:0x2000
	ds_read_b64_tr_b16 v[194:195], v211 offset:0x2800
	ds_read_b64_tr_b16 v[196:197], v211 offset:0x2200
	ds_read_b64_tr_b16 v[198:199], v211 offset:0x2a00
	ds_read_b64_tr_b16 v[200:201], v211 offset:0x2400
	ds_read_b64_tr_b16 v[202:203], v211 offset:0x2c00
	ds_read_b64_tr_b16 v[204:205], v211 offset:0x2600
	ds_read_b64_tr_b16 v[206:207], v211 offset:0x2e00
	v_fmamk_f32 v75, v75, 0x3e0293ee, v208
	v_exp_f32_e32 v74, v74
	v_add_f32_e32 v210, v72, v210
	v_permlane32_swap_b32_e32 v95, v97
	v_fmamk_f32 v76, v76, 0x3e0293ee, v208
	v_exp_f32_e32 v75, v75
	v_add_f32_e32 v210, v73, v210
	s_waitcnt lgkmcnt(8)
	v_mfma_f32_32x32x16_bf16 v[2:17], v[160:163], v[94:97], v[2:17]
	v_fmamk_f32 v77, v77, 0x3e0293ee, v208
	v_exp_f32_e32 v76, v76
	v_add_f32_e32 v210, v74, v210
	v_cvt_pk_bf16_f32 v73, v72, v73
	v_fmamk_f32 v78, v78, 0x3e0293ee, v208
	v_exp_f32_e32 v77, v77
	v_add_f32_e32 v210, v75, v210
	v_cvt_pk_bf16_f32 v72, v70, v71
	v_mfma_f32_32x32x16_bf16 v[18:33], v[164:167], v[94:97], v[18:33]
	v_fmamk_f32 v79, v79, 0x3e0293ee, v208
	v_exp_f32_e32 v78, v78
	v_add_f32_e32 v210, v76, v210
	v_cvt_pk_bf16_f32 v71, v68, v69
	v_fmamk_f32 v80, v80, 0x3e0293ee, v208
	v_exp_f32_e32 v79, v79
	v_add_f32_e32 v210, v77, v210
	v_cvt_pk_bf16_f32 v70, v66, v67
	v_mfma_f32_32x32x16_bf16 v[34:49], v[184:187], v[94:97], v[34:49]
	v_fmamk_f32 v81, v81, 0x3e0293ee, v208
	v_exp_f32_e32 v80, v80
	v_add_f32_e32 v210, v78, v210
	v_exp_f32_e32 v81, v81
	v_add_f32_e32 v210, v79, v210
	v_mfma_f32_32x32x16_bf16 v[50:65], v[188:191], v[94:97], v[50:65]
	ds_read_b64_tr_b16 v[160:161], v211 offset:0x3000
	ds_read_b64_tr_b16 v[162:163], v211 offset:0x3800
	ds_read_b64_tr_b16 v[164:165], v211 offset:0x3200
	ds_read_b64_tr_b16 v[166:167], v211 offset:0x3a00
	ds_read_b64_tr_b16 v[184:185], v211 offset:0x3400
	ds_read_b64_tr_b16 v[186:187], v211 offset:0x3c00
	ds_read_b64_tr_b16 v[188:189], v211 offset:0x3600
	ds_read_b64_tr_b16 v[190:191], v211 offset:0x3e00
	v_permlane32_swap_b32_e32 v70, v72
	v_add_f32_e32 v210, v80, v210
	v_permlane32_swap_b32_e32 v71, v73
	v_add_f32_e32 v210, v81, v210
	v_cvt_pk_bf16_f32 v81, v80, v81
	s_waitcnt lgkmcnt(8)
	v_mfma_f32_32x32x16_bf16 v[2:17], v[192:195], v[70:73], v[2:17]
	v_cvt_pk_bf16_f32 v80, v78, v79
	v_cvt_pk_bf16_f32 v79, v76, v77
	v_mfma_f32_32x32x16_bf16 v[18:33], v[196:199], v[70:73], v[18:33]
	v_cvt_pk_bf16_f32 v78, v74, v75
	v_mov_b32_e32 v168, v210
	v_mfma_f32_32x32x16_bf16 v[34:49], v[200:203], v[70:73], v[34:49]
	v_permlane32_swap_b32_e32 v78, v80
	v_permlane32_swap_b32_e32 v79, v81
	v_permlane32_swap_b32_e32 v210, v168
	v_mfma_f32_32x32x16_bf16 v[50:65], v[204:207], v[70:73], v[50:65]
	v_add_f32_e32 v168, v210, v168
	v_fmac_f32_e32 v168, v149, v144
	v_mov_b32_e32 v149, v168
	s_waitcnt lgkmcnt(6)
	v_mfma_f32_32x32x16_bf16 v[2:17], v[160:163], v[78:81], v[2:17]
	s_waitcnt lgkmcnt(4)
	v_mfma_f32_32x32x16_bf16 v[18:33], v[164:167], v[78:81], v[18:33]
	s_waitcnt lgkmcnt(2)
	v_mfma_f32_32x32x16_bf16 v[34:49], v[184:187], v[78:81], v[34:49]
	s_waitcnt lgkmcnt(0)
	v_mfma_f32_32x32x16_bf16 v[50:65], v[188:191], v[78:81], v[50:65]
	s_branch .LBB0_227

; DEVI void phase_attn(const Params& p, int layer, const int tid_) {
;   int* cnt = (int*)(p.ws + WS_MISC) + layer;
;   volatile int* slot = (volatile int*)(smem + ATT_SLOT);
;   for (;;) {
;     if (tid_ == 0) *slot = atomicAdd(cnt, 1);
;     __syncthreads();
;     const int item = __builtin_amdgcn_readfirstlane(*slot) + (layer == 0 ? 0 : IT_META);
;     __syncthreads();
;     if (item >= IT_TOTAL) break;
;     int tid2; asm volatile("v_mov_b32 %0, %1" : "=v"(tid2) : "v"(tid_));
;     attn_item(p, layer, item, tid2);
;   }
; }
.LBB0_263:
	s_setprio 0
	v_readlane_b32 s16, v254, 55
	v_readlane_b32 s30, v255, 5
	v_readlane_b32 s31, v255, 6
	v_readlane_b32 s14, v255, 7
	s_mov_b64 s[2:3], 0
	v_readlane_b32 s17, v254, 56
	v_readlane_b32 s18, v254, 57
	v_readlane_b32 s19, v254, 58
	v_readlane_b32 s20, v254, 59
	v_readlane_b32 s21, v254, 60
	v_readlane_b32 s22, v254, 61
	v_readlane_b32 s23, v254, 62
	v_readlane_b32 s24, v254, 63
	v_readlane_b32 s25, v255, 0
	v_readlane_b32 s26, v255, 1
	v_readlane_b32 s27, v255, 2
	v_readlane_b32 s28, v255, 3
	v_readlane_b32 s29, v255, 4
	v_readlane_b32 s15, v255, 8
	s_movk_i32 s30, 0x604f
	v_readlane_b32 s31, v255, 15
